# phase 11: blocks >= 256 run the RMSNorm part before the weight conversion (mixing bandwidth-bound and latency-bound work per CU)
# baseline (speedup 1.0000x reference)
.LBB0_1007:
	s_or_b64 exec, exec, s[0:1]
	v_mov_b32_e32 v10, v174
	v_readlane_b32 s0, v255, 42
	s_waitcnt lgkmcnt(0)
	s_barrier
	s_mov_b32 s101, 0
	s_cmp_lg_u32 s28, 0x200
	s_cbranch_scc1 .Lsw_conv
	s_cmp_lt_u32 s2, 0x100
	s_cbranch_scc1 .Lsw_conv
	s_mov_b32 s101, 1
	s_branch .LBB0_1064
.Lsw_conv2:
	v_mov_b32_e32 v10, v174
	v_readlane_b32 s0, v255, 42
	s_nop 1
.Lsw_conv:
	s_nop 0
	v_add_u32_e32 v11, s0, v10
	s_movk_i32 s0, 0x2000
	v_cmp_gt_i32_e32 vcc, s0, v11
	s_and_saveexec_b64 s[0:1], vcc
	s_cbranch_execz .LBB0_1014
	s_lshl_b32 s3, s28, 8
	v_readlane_b32 s4, v254, 19
	v_readlane_b32 s5, v254, 20
	s_add_u32 s4, s4, 0x10000
	v_readlane_b32 s52, v254, 21
	s_addc_u32 s5, s5, 0
	v_readlane_b32 s58, v254, 27
	v_readlane_b32 s59, v254, 28
	s_add_u32 s6, s58, 0x20000
	v_lshlrev_b32_e32 v0, 3, v10
	s_addc_u32 s7, s59, 0
	s_waitcnt vmcnt(10)
	v_lshl_add_u32 v12, s2, 11, v0
	s_lshl_b32 s12, s28, 11
	s_mov_b64 s[8:9], 0
	v_mov_b32_e32 v1, 0
	s_movk_i32 s13, 0x800
	v_readlane_b32 s53, v254, 22
	v_readlane_b32 s54, v254, 23
	v_readlane_b32 s55, v254, 24
	v_readlane_b32 s56, v254, 25
	v_readlane_b32 s57, v254, 26
	v_readlane_b32 s60, v254, 29
	v_readlane_b32 s61, v254, 30
	v_readlane_b32 s62, v254, 31
	v_readlane_b32 s63, v254, 32
	v_readlane_b32 s64, v254, 33
	v_readlane_b32 s65, v254, 34
	v_readlane_b32 s66, v254, 35
	v_readlane_b32 s67, v254, 36
	s_branch .LBB0_1010

.LBB0_1064:
	s_cmp_eq_u32 s101, 2
	s_cbranch_scc1 .Lsw_bar
	v_mov_b32_e32 v0, v174
	v_mov_b32_e32 v1, v174
	v_readlane_b32 s0, v254, 55
	v_ashrrev_i32_e32 v1, 6, v1
	s_movk_i32 s3, 0x4400
	v_add_u32_e32 v50, s0, v1
	v_cmp_gt_i32_e32 vcc, s3, v50
	s_and_saveexec_b64 s[4:5], vcc
	s_cbranch_execz .LBB0_1075
	v_lshlrev_b32_e32 v0, 2, v0
	v_and_b32_e32 v0, 0xfc, v0
	v_readlane_b32 s52, v254, 39
	v_mov_b32_e32 v41, 0
	v_lshlrev_b32_e32 v40, 2, v0
	v_readlane_b32 s66, v254, 53
	v_readlane_b32 s67, v254, 54
	s_mov_b64 s[0:1], 0x1000
	v_mbcnt_hi_u32_b32 v1, -1, v175
	v_lshl_add_u64 v[2:3], s[66:67], 0, v[40:41]
	v_lshl_add_u64 v[42:43], v[2:3], 0, s[0:1]
	v_and_b32_e32 v3, 64, v1
	v_xor_b32_e32 v2, 16, v1
	v_add_u32_e32 v3, 64, v3
	v_cmp_lt_i32_e32 vcc, v2, v3
	v_lshlrev_b32_e32 v40, 1, v0
	s_lshl_b32 s10, s28, 2
	v_cndmask_b32_e32 v2, v1, v2, vcc
	v_lshlrev_b32_e32 v47, 2, v2
	v_xor_b32_e32 v2, 32, v1
	v_cmp_lt_i32_e32 vcc, v2, v3
	v_lshl_add_u64 v[44:45], s[38:39], 0, v[40:41]
	s_mov_b64 s[8:9], 0
	v_cndmask_b32_e32 v1, v1, v2, vcc
	v_lshlrev_b32_e32 v62, 2, v1
	s_movk_i32 s11, 0x43ff
	v_lshlrev_b32_e32 v40, 2, v0
	v_mov_b32_e32 v46, 0x358637bd
	s_mov_b32 s12, 0x800000
	v_readlane_b32 s53, v254, 40
	v_readlane_b32 s54, v254, 41
	v_readlane_b32 s55, v254, 42
	v_readlane_b32 s56, v254, 43
	v_readlane_b32 s57, v254, 44
	v_readlane_b32 s58, v254, 45
	v_readlane_b32 s59, v254, 46
	v_readlane_b32 s60, v254, 47
	v_readlane_b32 s61, v254, 48
	v_readlane_b32 s62, v254, 49
	v_readlane_b32 s63, v254, 50
	v_readlane_b32 s64, v254, 51
	v_readlane_b32 s65, v254, 52
	s_branch .LBB0_1067

.LBB0_1075:
	s_or_b64 exec, exec, s[4:5]
	s_cmp_eq_u32 s101, 1
	s_cbranch_scc0 .Lsw_bar
	s_mov_b32 s101, 2
	s_branch .Lsw_conv2
